# L2 warm-up loads: GLA3 touches the next item's q/k/v/decay/state lines while the current item computes; adaLN GEMV touches its 7 later weight rows at the top of each k-group
# baseline (speedup 1.0000x reference)
; DI unsigned pk_bf16(float lo, float hi) { unsigned r; asm("v_cvt_pk_bf16_f32 %0, %1, %2" : "=v"(r) : "v"(lo), "v"(hi)); return r; }
; DI float lo_f(unsigned w) { return __uint_as_float(w << 16); }
; DI void gla_pass3_item(unsigned char* ws, const float* wa2, const float* gba, const float* gnorm, unsigned char* lds, int cid, int hh) {
;     ...
;     {
;         const int c = tid >> 3, d0 = (tid & 7) * 4, e0 = (tid & 7) * 8;
;         const bf16_t* rp = P + ((size_t)cid * 64 + c) * IN_DIM;
;         const float* GBi = (const float*)(ws + WS_M2) + (size_t)NCH * 4 * 2 * 2048 + ((size_t)cid * 4 + hh) * 4096;
;         const u32x2 qv = *(const u32x2*)(rp + C_GQ + hh * 32 + d0), kv = *(const u32x2*)(rp + C_GK + hh * 32 + d0);
;         const f32x4 bfv = *(const f32x4*)(GBi + c * 32 + d0), bbv = *(const f32x4*)(GBi + 2048 + c * 32 + d0);
;         const u32x4 vv = *(const u32x4*)(rp + C_GV + hh * 64 + e0);
;         const int sd = tid >> 8, d = (tid & 255) >> 3;
;         const float* GSp = (const float*)(ws + WS_M2) + (((size_t)cid * 4 + hh) * 2 + sd) * 2048 + d * 64 + e0;
;         const f32x4 s0 = *(const f32x4*)GSp, s1 = *(const f32x4*)(GSp + 4);
;         __syncthreads();
;         const float qs = 0.17677669529663687f;
;         const float qq[4] = {lo_f(qv[0]) * qs, hi_f(qv[0]) * qs, lo_f(qv[1]) * qs, hi_f(qv[1]) * qs};
;         const float kk[4] = {lo_f(kv[0]), hi_f(kv[0]), lo_f(kv[1]), hi_f(kv[1])};
;         float qf[4], kf[4], qb[4], kb[4];
; #pragma unroll
;         for (int j = 0; j < 4; ++j) { qf[j] = qq[j] * __expf(bfv[j]); kf[j] = kk[j] * __expf(-bfv[j]); qb[j] = qq[j] * __expf(bbv[j]); kb[j] = kk[j] * __expf(-bbv[j]); }
;         u32x2 o;
;         o[0] = pk_bf16(qf[0], qf[1]); o[1] = pk_bf16(qf[2], qf[3]); *(u32x2*)(QT + c * 40 + d0) = o;
;         o[0] = pk_bf16(kf[0], kf[1]); o[1] = pk_bf16(kf[2], kf[3]); *(u32x2*)(KT + c * 40 + d0) = o;
;         o[0] = pk_bf16(qb[0], qb[1]); o[1] = pk_bf16(qb[2], qb[3]); *(u32x2*)(QT + 64 * 40 + c * 40 + d0) = o;
;         o[0] = pk_bf16(kb[0], kb[1]); o[1] = pk_bf16(kb[2], kb[3]); *(u32x2*)(KT + 64 * 40 + c * 40 + d0) = o;
;         *(u32x4*)(VT + c * 72 + e0) = vv;
;         {   u32x4 so; so[0] = pk_bf16(s0[0], s0[1]); so[1] = pk_bf16(s0[2], s0[3]); so[2] = pk_bf16(s1[0], s1[1]); so[3] = pk_bf16(s1[2], s1[3]);
;             *(u32x4*)(ST + sd * 32 * 72 + d * 72 + e0) = so; }
.LBB0_129:
	s_load_dwordx2 s[6:7], s[0:1], 0x70
	s_waitcnt lgkmcnt(0)
	s_load_dwordx2 s[6:7], s[0:1], 0x78
	s_load_dwordx2 s[42:43], s[0:1], 0x80
	s_waitcnt lgkmcnt(0)
	s_ashr_i32 s6, s33, 2
	v_mov_b32_e32 v20, v176
	s_ashr_i32 s7, s6, 31
	v_ashrrev_i32_e32 v2, 3, v20
	s_lshl_b64 s[16:17], s[6:7], 6
	v_ashrrev_i32_e32 v3, 31, v2
	v_lshl_add_u64 v[4:5], s[16:17], 0, v[2:3]
	v_mov_b64_e32 v[6:7], s[76:77]
	s_and_b32 s2, s33, 3
	v_mad_u64_u32 v[14:15], s[8:9], v4, s28, v[6:7]
	s_lshl_b64 s[6:7], s[6:7], 16
	s_lshl_b32 s8, s2, 14
	s_or_b32 s6, s6, s8
	s_add_u32 s8, s5, s6
	v_lshlrev_b32_e32 v4, 5, v2
	v_and_b32_e32 v16, 7, v20
	v_mad_i32_i24 v15, v5, s28, v15
	s_addc_u32 s9, s22, s7
	v_ashrrev_i32_e32 v5, 31, v4
	v_lshl_add_u64 v[6:7], v[4:5], 2, s[8:9]
	v_lshlrev_b32_e32 v4, 4, v16
	v_mov_b32_e32 v5, v1
	v_lshl_add_u64 v[10:11], v[6:7], 0, v[4:5]
	v_mov_b64_e32 v[80:81], v[10:11]
	s_lshl_b32 s72, s2, 6
	v_lshlrev_b32_e32 v0, 3, v16
	flat_load_dwordx4 v[6:9], v[10:11]
	v_lshl_add_u64 v[12:13], v[14:15], 0, s[72:73]
	v_add_co_u32_e32 v10, vcc, s61, v10
	v_lshl_add_u64 v[12:13], v[12:13], 0, v[0:1]
	v_mov_b64_e32 v[82:83], v[12:13]
	s_nop 0
	v_addc_co_u32_e32 v11, vcc, 0, v11, vcc
	v_mov_b64_e32 v[84:85], v[10:11]
	flat_load_dwordx2 v[30:31], v[12:13] offset:2048
	flat_load_dwordx2 v[32:33], v[12:13] offset:2304
	s_mov_b32 s9, s73
	flat_load_dwordx4 v[10:13], v[10:11]
	v_ashrrev_i32_e32 v18, 8, v20
	s_lshl_b32 s8, s2, 7
	v_ashrrev_i32_e32 v19, 31, v18
	s_add_u32 s6, s34, s6
	v_lshl_add_u64 v[14:15], v[14:15], 0, s[8:9]
	v_bfe_u32 v21, v20, 3, 5
	v_lshlrev_b32_e32 v24, 5, v16
	v_lshlrev_b64 v[16:17], 13, v[18:19]
	s_addc_u32 s7, s35, s7
	v_lshl_add_u64 v[14:15], v[14:15], 0, v[4:5]
	v_mov_b64_e32 v[86:87], v[14:15]
	v_mov_b32_e32 v23, v1
	v_lshlrev_b32_e32 v22, 8, v21
	v_lshl_add_u64 v[26:27], s[6:7], 0, v[16:17]
	flat_load_dwordx4 v[14:17], v[14:15] offset:2560
	v_mov_b32_e32 v25, v1
	v_lshl_add_u64 v[22:23], v[26:27], 0, v[22:23]
	v_lshl_add_u64 v[26:27], v[22:23], 0, v[24:25]
	v_mov_b64_e32 v[88:89], v[26:27]
	flat_load_dwordx4 v[22:25], v[26:27]
	s_nop 0
	flat_load_dwordx4 v[26:29], v[26:27] offset:16
	s_add_i32 s2, s33, 0x100
	s_cmp_lt_i32 s2, s4
	s_cbranch_scc0 .Lgla3_nopf
	v_add_co_u32_e32 v92, vcc, 0x400000, v80
	s_nop 1
	v_addc_co_u32_e32 v93, vcc, 0, v81, vcc
	global_load_dword v94, v[92:93], off
	v_add_co_u32_e32 v92, vcc, 0x400000, v84
	s_nop 1
	v_addc_co_u32_e32 v93, vcc, 0, v85, vcc
	global_load_dword v94, v[92:93], off
	v_add_co_u32_e32 v92, vcc, 0x2640000, v82
	s_nop 1
	v_addc_co_u32_e32 v93, vcc, 0, v83, vcc
	global_load_dword v94, v[92:93], off offset:2048
	global_load_dword v94, v[92:93], off offset:2304
	v_add_co_u32_e32 v92, vcc, 0x2640000, v86
	s_nop 1
	v_addc_co_u32_e32 v93, vcc, 0, v87, vcc
	global_load_dword v94, v[92:93], off offset:2560
	v_add_co_u32_e32 v92, vcc, 0x400000, v88
	s_nop 1
	v_addc_co_u32_e32 v93, vcc, 0, v89, vcc
	global_load_dword v94, v[92:93], off
.Lgla3_nopf:
	s_movk_i32 s2, 0x50
	s_waitcnt lgkmcnt(0)
	s_barrier
	v_and_b32_e32 v3, 15, v20
	v_cmp_gt_u32_e32 vcc, s71, v20
	s_waitcnt vmcnt(0)
	v_mul_f32_e32 v5, 0x3fb8aa3b, v6
	v_mul_f32_e32 v6, 0xbfb8aa3b, v6
	v_mul_f32_e32 v19, 0x3fb8aa3b, v7
	v_mul_f32_e32 v7, 0xbfb8aa3b, v7
	v_exp_f32_e32 v6, v6
	v_exp_f32_e32 v19, v19
	v_exp_f32_e32 v7, v7
	v_lshlrev_b32_e32 v34, 16, v30
	v_and_b32_e32 v30, 0xffff0000, v30
	v_mul_f32_e32 v39, 0x3fb8aa3b, v11
	v_mul_f32_e32 v11, 0xbfb8aa3b, v11
	v_exp_f32_e32 v11, v11
	v_lshlrev_b32_e32 v36, 16, v32
	v_and_b32_e32 v32, 0xffff0000, v32
	v_mul_f32_e32 v30, 0x3e3504f3, v30
	v_mul_f32_e32 v38, 0x3fb8aa3b, v10
	v_mul_f32_e32 v10, 0xbfb8aa3b, v10
	v_mul_f32_e32 v40, v6, v36
	v_mul_f32_e32 v6, v30, v19
	v_mul_f32_e32 v19, v7, v32
	v_mul_f32_e32 v7, 0x3fb8aa3b, v8
	v_mul_f32_e32 v8, 0xbfb8aa3b, v8
	v_exp_f32_e32 v10, v10
	v_mul_f32_e32 v11, v11, v32
	v_exp_f32_e32 v8, v8
	v_mul_f32_e32 v32, 0x3fb8aa3b, v12
	v_exp_f32_e32 v7, v7
	v_exp_f32_e32 v32, v32
	v_lshlrev_b32_e32 v35, 16, v31
	v_lshlrev_b32_e32 v37, 16, v33
	v_exp_f32_e32 v5, v5
	v_mul_f32_e32 v35, 0x3e3504f3, v35
	v_mul_f32_e32 v10, v10, v36
	v_mul_f32_e32 v36, v8, v37
	v_mul_f32_e32 v8, 0x3fb8aa3b, v9
	v_mul_f32_e32 v7, v35, v7
	v_mul_f32_e32 v32, v35, v32
	v_exp_f32_e32 v8, v8
	v_mul_f32_e32 v9, 0xbfb8aa3b, v9
	v_mul_f32_e32 v35, 0x3fb8aa3b, v13
	v_exp_f32_e32 v9, v9
	v_exp_f32_e32 v35, v35
	v_and_b32_e32 v31, 0xffff0000, v31
	v_mul_f32_e32 v34, 0x3e3504f3, v34
	v_mul_f32_e32 v12, 0xbfb8aa3b, v12
	v_mul_f32_e32 v13, 0xbfb8aa3b, v13
	v_mul_f32_e32 v31, 0x3e3504f3, v31
	v_exp_f32_e32 v38, v38
	v_exp_f32_e32 v39, v39
	v_mul_f32_e32 v5, v34, v5
	v_exp_f32_e32 v12, v12
	v_exp_f32_e32 v13, v13
	v_and_b32_e32 v33, 0xffff0000, v33
	v_mul_f32_e32 v8, v31, v8
	v_cvt_pk_bf16_f32 v6, v5, v6
	v_mul_lo_u32 v5, v2, s2
	v_mul_f32_e32 v9, v9, v33
	v_mul_f32_e32 v31, v31, v35
	v_cvt_pk_bf16_f32 v7, v7, v8
	v_add3_u32 v35, 0, v5, v0
	v_cvt_pk_bf16_f32 v8, v40, v19
	v_add3_u32 v19, s10, v5, v0
	v_cvt_pk_bf16_f32 v9, v36, v9
	ds_write_b64 v19, v[8:9]
	v_add_u32_e32 v19, 0x100, v35
	v_add3_u32 v0, s11, v5, v0
	v_mul_f32_e32 v34, v34, v38
	v_mul_f32_e32 v30, v30, v39
	v_mul_f32_e32 v12, v12, v37
	v_mul_f32_e32 v13, v13, v33
	v_cvt_pk_bf16_f32 v8, v34, v30
	v_cvt_pk_bf16_f32 v9, v32, v31
	ds_write2st64_b64 v19, v[6:7], v[8:9] offset0:116 offset1:126
	v_cvt_pk_bf16_f32 v6, v10, v11
	v_cvt_pk_bf16_f32 v7, v12, v13
	ds_write_b64 v0, v[6:7]
	v_mul_lo_u32 v0, v2, s62
	v_add3_u32 v0, s69, v0, v4
	ds_write_b128 v0, v[14:17]
	v_mov_b32_e32 v0, s14
	s_movk_i32 s2, 0x1200
	v_mad_i32_i24 v10, v18, s2, v0
	v_mul_u32_u24_e32 v0, 0x90, v21
	v_add3_u32 v0, v10, v0, v4
	v_cvt_pk_bf16_f32 v6, v22, v23
	v_cvt_pk_bf16_f32 v7, v24, v25
	v_cvt_pk_bf16_f32 v8, v26, v27
	v_cvt_pk_bf16_f32 v9, v28, v29
	ds_write_b128 v0, v[6:9]
	v_mul_i32_i24_e32 v0, 0xa00, v18
	v_lshlrev_b32_e32 v0, 1, v0
	v_add_u32_e32 v6, 0, v0
	v_add_u32_e32 v2, s10, v0
	v_mov_b32_e32 v0, s15
	s_movk_i32 s2, 0x2400
	v_mad_i32_i24 v11, v18, s2, v0
	v_lshrrev_b32_e32 v0, 2, v20
	v_and_or_b32 v0, v0, 48, v3
	v_and_b32_e32 v19, 48, v20
	v_mul_u32_u24_e32 v3, 0x50, v3
	v_add3_u32 v12, v2, v19, v3
	s_waitcnt lgkmcnt(0)
	s_barrier
; DI unsigned pk_bf16(float lo, float hi) { unsigned r; asm("v_cvt_pk_bf16_f32 %0, %1, %2" : "=v"(r) : "v"(lo), "v"(hi)); return r; }
; DI void gla_pass3_item(unsigned char* ws, const float* wa2, const float* gba, const float* gnorm, unsigned char* lds, int cid, int hh) {
;     ...
;     const bf16_t* QTd = QT + dir * 64 * 40; const bf16_t* KTd = KT + dir * 64 * 40; bf16_t* ATTd = ATT + dir * 64 * 72; const bf16_t* STd = ST + dir * 32 * 72;
;     {
;         const bf16x8 qfrag = *(const bf16x8*)(QTd + (mt * 16 + fr) * 40 + fq * 8);
;         const int i = mt * 16 + fr;
; #pragma unroll
;         for (int nt = 0; nt < 4; ++nt) {
;             const bf16x8 kfrag = *(const bf16x8*)(KTd + (nt * 16 + fr) * 40 + fq * 8);
;             f32x4 a = (f32x4){0.f, 0.f, 0.f, 0.f};
;             a = __builtin_amdgcn_mfma_f32_16x16x32_bf16(kfrag, qfrag, a, 0, 0, 0);
;             float r[4];
; #pragma unroll
;             for (int jq = 0; jq < 4; ++jq) { const int j = nt * 16 + fq * 4 + jq; const int dji = dir ? (j - i) : (i - j); r[jq] = (dji >= 0) ? a[jq] : 0.f; }
;             u32x2 o; o[0] = pk_bf16(r[0], r[1]); o[1] = pk_bf16(r[2], r[3]);
;             *(u32x2*)(ATTd + (mt * 16 + fr) * 72 + nt * 16 + fq * 4) = o;
;         }
;     }
;     __syncthreads();
	ds_read_b128 v[2:5], v12
	v_mul_u32_u24_e32 v7, 0x50, v0
	v_add3_u32 v26, v6, v7, v19
	ds_read_b128 v[6:9], v26 offset:59648
	v_bfe_u32 v33, v20, 4, 2
	v_lshlrev_b32_e32 v13, 3, v33
	v_lshlrev_b32_e32 v21, 2, v33
	v_mul_u32_u24_e32 v14, 0x90, v0
	v_add3_u32 v11, v11, v14, v13
	v_sub_u32_e32 v14, v21, v0
	v_sub_u32_e32 v15, v0, v21
	s_waitcnt lgkmcnt(0)
	v_mfma_f32_16x16x32_bf16 v[2:5], v[2:5], v[6:9], 0
	v_cndmask_b32_e32 v14, v14, v15, vcc
	v_cmp_lt_i32_e64 s[40:41], -1, v14
	v_or_b32_e32 v14, 1, v21
	v_sub_u32_e32 v15, v14, v0
	v_sub_u32_e32 v14, v0, v14
	v_cndmask_b32_e32 v14, v15, v14, vcc
	s_nop 1
	v_cndmask_b32_e64 v2, 0, v2, s[40:41]
	v_cmp_lt_i32_e64 s[40:41], -1, v14
	v_or_b32_e32 v14, 2, v21
	v_sub_u32_e32 v15, v14, v0
	v_sub_u32_e32 v14, v0, v14
	v_cndmask_b32_e32 v14, v15, v14, vcc
	v_cndmask_b32_e64 v3, 0, v3, s[40:41]
	v_cmp_lt_i32_e64 s[40:41], -1, v14
	v_or_b32_e32 v14, 3, v21
	v_sub_u32_e32 v15, v14, v0
	v_sub_u32_e32 v14, v0, v14
	v_cndmask_b32_e32 v14, v15, v14, vcc
	v_cndmask_b32_e64 v4, 0, v4, s[40:41]
	v_cmp_lt_i32_e64 s[40:41], -1, v14
	v_cvt_pk_bf16_f32 v2, v2, v3
	v_or_b32_e32 v14, 16, v21
	v_sub_u32_e32 v15, v14, v0
	v_cndmask_b32_e64 v5, 0, v5, s[40:41]
	v_cvt_pk_bf16_f32 v3, v4, v5
	ds_write_b64 v11, v[2:3]
	ds_read_b128 v[2:5], v12 offset:1280
	v_sub_u32_e32 v14, v0, v14
	s_waitcnt lgkmcnt(0)
	v_mfma_f32_16x16x32_bf16 v[2:5], v[2:5], v[6:9], 0
	v_cndmask_b32_e32 v14, v15, v14, vcc
	v_cmp_lt_i32_e64 s[40:41], -1, v14
	v_or_b32_e32 v14, 17, v21
	v_sub_u32_e32 v15, v14, v0
	v_sub_u32_e32 v14, v0, v14
	v_cndmask_b32_e32 v14, v15, v14, vcc
	s_nop 1
	v_cndmask_b32_e64 v2, 0, v2, s[40:41]
	v_cmp_lt_i32_e64 s[40:41], -1, v14
	v_or_b32_e32 v14, 18, v21
	v_sub_u32_e32 v15, v14, v0
	v_sub_u32_e32 v14, v0, v14
	v_cndmask_b32_e32 v14, v15, v14, vcc
	v_cndmask_b32_e64 v3, 0, v3, s[40:41]
	v_cmp_lt_i32_e64 s[40:41], -1, v14
	v_or_b32_e32 v14, 19, v21
	v_sub_u32_e32 v15, v14, v0
	v_sub_u32_e32 v14, v0, v14
	v_cndmask_b32_e32 v14, v15, v14, vcc
	v_cndmask_b32_e64 v4, 0, v4, s[40:41]
	v_cmp_lt_i32_e64 s[40:41], -1, v14
	v_cvt_pk_bf16_f32 v2, v2, v3
	v_or_b32_e32 v14, 32, v21
	v_sub_u32_e32 v15, v14, v0
	v_cndmask_b32_e64 v5, 0, v5, s[40:41]
	v_cvt_pk_bf16_f32 v3, v4, v5
	ds_write_b64 v11, v[2:3] offset:32
	ds_read_b128 v[2:5], v12 offset:2560
	v_sub_u32_e32 v14, v0, v14
	s_waitcnt lgkmcnt(0)
	v_mfma_f32_16x16x32_bf16 v[2:5], v[2:5], v[6:9], 0
	v_cndmask_b32_e32 v14, v15, v14, vcc
	v_cmp_lt_i32_e64 s[40:41], -1, v14
	v_or_b32_e32 v14, 33, v21
	v_sub_u32_e32 v15, v14, v0
	v_sub_u32_e32 v14, v0, v14
	v_cndmask_b32_e32 v14, v15, v14, vcc
	s_nop 1
	v_cndmask_b32_e64 v2, 0, v2, s[40:41]
	v_cmp_lt_i32_e64 s[40:41], -1, v14
	v_or_b32_e32 v14, 34, v21
	v_sub_u32_e32 v15, v14, v0
	v_sub_u32_e32 v14, v0, v14
	v_cndmask_b32_e32 v14, v15, v14, vcc
	v_cndmask_b32_e64 v3, 0, v3, s[40:41]
	v_cmp_lt_i32_e64 s[40:41], -1, v14
	v_or_b32_e32 v14, 35, v21
	v_sub_u32_e32 v15, v14, v0
	v_sub_u32_e32 v14, v0, v14
	v_cndmask_b32_e32 v14, v15, v14, vcc
	v_cndmask_b32_e64 v4, 0, v4, s[40:41]
	v_cmp_lt_i32_e64 s[40:41], -1, v14
	v_cvt_pk_bf16_f32 v2, v2, v3
	s_nop 1
	v_cndmask_b32_e64 v5, 0, v5, s[40:41]
	v_cvt_pk_bf16_f32 v3, v4, v5
	ds_write_b64 v11, v[2:3] offset:64
	ds_read_b128 v[2:5], v12 offset:3840
	s_waitcnt lgkmcnt(0)
	v_mfma_f32_16x16x32_bf16 v[2:5], v[2:5], v[6:9], 0
	v_or_b32_e32 v6, 48, v21
	v_sub_u32_e32 v7, v6, v0
	v_sub_u32_e32 v6, v0, v6
	v_cndmask_b32_e32 v6, v7, v6, vcc
	v_cmp_lt_i32_e64 s[40:41], -1, v6
	v_or_b32_e32 v6, 49, v21
	v_sub_u32_e32 v7, v6, v0
	v_sub_u32_e32 v6, v0, v6
	v_cndmask_b32_e32 v6, v7, v6, vcc
	v_cndmask_b32_e64 v2, 0, v2, s[40:41]
	v_cmp_lt_i32_e64 s[40:41], -1, v6
	v_or_b32_e32 v6, 50, v21
	v_sub_u32_e32 v7, v6, v0
	v_sub_u32_e32 v6, v0, v6
	v_cndmask_b32_e32 v6, v7, v6, vcc
	v_cndmask_b32_e64 v3, 0, v3, s[40:41]
	v_cmp_lt_i32_e64 s[40:41], -1, v6
	v_or_b32_e32 v6, 51, v21
	v_sub_u32_e32 v7, v6, v0
	v_sub_u32_e32 v6, v0, v6
	v_cndmask_b32_e32 v6, v7, v6, vcc
	v_cndmask_b32_e64 v4, 0, v4, s[40:41]
	v_cmp_lt_i32_e64 s[40:41], -1, v6
	v_cvt_pk_bf16_f32 v2, v2, v3
	s_nop 1
	v_cndmask_b32_e64 v5, 0, v5, s[40:41]
	v_cvt_pk_bf16_f32 v3, v4, v5
	ds_write_b64 v11, v[2:3] offset:96
	v_bfe_u32 v2, v20, 2, 2
	v_or_b32_e32 v2, v13, v2
	v_mul_u32_u24_e32 v2, 0x48, v2
	v_lshlrev_b32_e32 v12, 1, v2
	v_lshlrev_b32_e32 v2, 3, v20
	v_and_b32_e32 v33, 24, v2
	v_add_u32_e32 v32, 0x240, v12
	v_add_u32_e32 v2, s69, v33
	v_add_u32_e32 v38, v2, v12
	v_add_u32_e32 v2, v2, v32
	s_waitcnt lgkmcnt(0)
	s_barrier
; #define LAS __attribute__((address_space(3)))
; DI void gla_pass3_item(unsigned char* ws, const float* wa2, const float* gba, const float* gnorm, unsigned char* lds, int cid, int hh) {
;     ...
;     f32x4 o4[4];
;     {
;         const bf16x8 af0 = *(const bf16x8*)(ATTd + (mt * 16 + fr) * 72 + fq * 8), af1 = *(const bf16x8*)(ATTd + (mt * 16 + fr) * 72 + 32 + fq * 8);
;         const bf16x8 qfrag = *(const bf16x8*)(QTd + (mt * 16 + fr) * 40 + fq * 8);
; #pragma unroll
;         for (int nt = 0; nt < 4; ++nt) {
;             const int trc = nt * 16 + 4 * (fr & 3), trr = fq * 8 + (fr >> 2);
;             const s16x4 v0a = __builtin_amdgcn_ds_read_tr16_b64_v4i16((LAS s16x4*)(VT + (trr) * 72 + trc)), v0b = __builtin_amdgcn_ds_read_tr16_b64_v4i16((LAS s16x4*)(VT + (trr + 4) * 72 + trc));
;             const s16x4 v1a = __builtin_amdgcn_ds_read_tr16_b64_v4i16((LAS s16x4*)(VT + (32 + trr) * 72 + trc)), v1b = __builtin_amdgcn_ds_read_tr16_b64_v4i16((LAS s16x4*)(VT + (32 + trr + 4) * 72 + trc));
;             const s16x4 sfa = __builtin_amdgcn_ds_read_tr16_b64_v4i16((LAS s16x4*)(STd + (trr) * 72 + trc)), sfb = __builtin_amdgcn_ds_read_tr16_b64_v4i16((LAS s16x4*)(STd + (trr + 4) * 72 + trc));
;             const bf16x8 v0 = __builtin_shufflevector(v0a, v0b, 0, 1, 2, 3, 4, 5, 6, 7), v1 = __builtin_shufflevector(v1a, v1b, 0, 1, 2, 3, 4, 5, 6, 7), sf = __builtin_shufflevector(sfa, sfb, 0, 1, 2, 3, 4, 5, 6, 7);
;             f32x4 a = (f32x4){0.f, 0.f, 0.f, 0.f};
;             a = __builtin_amdgcn_mfma_f32_16x16x32_bf16(v0, af0, a, 0, 0, 0);
;             a = __builtin_amdgcn_mfma_f32_16x16x32_bf16(v1, af1, a, 0, 0, 0);
;             a = __builtin_amdgcn_mfma_f32_16x16x32_bf16(sf, qfrag, a, 0, 0, 0);
;             o4[nt] = a;
;         }
;     }
;     if (dir == 1) {
; #pragma unroll
;         for (int nt = 0; nt < 4; ++nt) {
;             float* ob = OB + (mt * 16 + fr) * 66 + nt * 16 + fq * 4;
;             *(f32x2*)ob = (f32x2){o4[nt][0], o4[nt][1]}; *(f32x2*)(ob + 2) = (f32x2){o4[nt][2], o4[nt][3]};
;         }
;     }
	ds_read_b64_tr_b16 v[4:5], v2
	ds_read_b64_tr_b16 v[2:3], v38
	v_add_u32_e32 v11, v11, v13
	ds_read_b128 v[14:17], v11
	ds_read_b64_tr_b16 v[6:7], v38 offset:4608
	ds_read_b64_tr_b16 v[8:9], v38 offset:5184
	ds_read_b128 v[22:25], v11 offset:64
	v_add3_u32 v39, v10, v12, v33
	ds_read_b64_tr_b16 v[12:13], v39 offset:576
	ds_read_b64_tr_b16 v[10:11], v39
	s_waitcnt lgkmcnt(5)
	v_mfma_f32_16x16x32_bf16 v[2:5], v[2:5], v[14:17], 0
	ds_read_b128 v[26:29], v26 offset:59648
	ds_read_b64_tr_b16 v[30:31], v38 offset:32
	v_add3_u32 v40, s69, v32, v33
	v_cmp_eq_u32_e64 s[40:41], 1, v18
	s_waitcnt lgkmcnt(4)
	v_mfma_f32_16x16x32_bf16 v[2:5], v[6:9], v[22:25], v[2:5]
	v_mul_u32_u24_e32 v18, 0x108, v0
	v_add3_u32 v18, 0, v18, v19
	s_waitcnt lgkmcnt(1)
	v_mfma_f32_16x16x32_bf16 v[6:9], v[10:13], v[26:29], v[2:5]
	ds_read_b64_tr_b16 v[32:33], v40 offset:32
	s_nop 2
	ds_read_b64_tr_b16 v[2:3], v38 offset:4640
	s_waitcnt lgkmcnt(1)
	v_mfma_f32_16x16x32_bf16 v[10:13], v[30:33], v[14:17], 0
	ds_read_b64_tr_b16 v[4:5], v38 offset:5216
	ds_read_b64_tr_b16 v[30:31], v39 offset:32
	ds_read_b64_tr_b16 v[32:33], v39 offset:608
	ds_read_b64_tr_b16 v[34:35], v40 offset:64
	s_waitcnt lgkmcnt(3)
	v_mfma_f32_16x16x32_bf16 v[2:5], v[2:5], v[22:25], v[10:13]
	s_waitcnt lgkmcnt(1)
	v_mfma_f32_16x16x32_bf16 v[10:13], v[30:33], v[26:29], v[2:5]
	ds_read_b64_tr_b16 v[32:33], v38 offset:64
	s_nop 4
	ds_read_b64_tr_b16 v[2:3], v38 offset:4672
	s_waitcnt lgkmcnt(1)
	v_mfma_f32_16x16x32_bf16 v[30:33], v[32:35], v[14:17], 0
	ds_read_b64_tr_b16 v[4:5], v38 offset:5248
	ds_read_b64_tr_b16 v[34:35], v39 offset:64
	ds_read_b64_tr_b16 v[36:37], v39 offset:640
	s_waitcnt lgkmcnt(2)
	v_mfma_f32_16x16x32_bf16 v[2:5], v[2:5], v[22:25], v[30:33]
	s_waitcnt lgkmcnt(0)
	v_mfma_f32_16x16x32_bf16 v[2:5], v[34:37], v[26:29], v[2:5]
	s_nop 0
	ds_read_b64_tr_b16 v[30:31], v38 offset:96
	ds_read_b64_tr_b16 v[32:33], v40 offset:96
	ds_read_b64_tr_b16 v[34:35], v38 offset:4704
	s_waitcnt lgkmcnt(1)
	v_mfma_f32_16x16x32_bf16 v[14:17], v[30:33], v[14:17], 0
	ds_read_b64_tr_b16 v[36:37], v38 offset:5280
	ds_read_b64_tr_b16 v[30:31], v39 offset:96
	ds_read_b64_tr_b16 v[32:33], v39 offset:672
	s_waitcnt lgkmcnt(2)
	v_mfma_f32_16x16x32_bf16 v[14:17], v[34:37], v[22:25], v[14:17]
	s_waitcnt lgkmcnt(0)
	v_mfma_f32_16x16x32_bf16 v[14:17], v[30:33], v[26:29], v[14:17]
	s_and_saveexec_b64 s[20:21], s[40:41]
	s_cbranch_execz .LBB0_131
	ds_write2_b64 v18, v[6:7], v[8:9] offset1:1
	ds_write2_b64 v18, v[10:11], v[12:13] offset0:8 offset1:9
	ds_write2_b64 v18, v[2:3], v[4:5] offset0:16 offset1:17
	s_nop 2
	ds_write2_b64 v18, v[14:15], v[16:17] offset0:24 offset1:25

; DI void phase_ada(const float* c_in, const float* cctx_in, const float* w_ada, const float* b_ada, unsigned char* ws, unsigned char* lds) {
;     ...
; #pragma unroll 8
;         for (int k = kg * 64; k < kg * 64 + 64; ++k) {
;             const f32x4 w = __builtin_nontemporal_load((const f32x4*)(W + (size_t)k * 6144));
; #pragma unroll
;             for (int r = 0; r < 9; ++r) { const float sv = sc[r * 1024 + k]; acc[r][0] += sv * w[0]; acc[r][1] += sv * w[1]; acc[r][2] += sv * w[2]; acc[r][3] += sv * w[3]; }
.LBB0_182:
	v_lshl_add_u64 v[48:49], v[46:47], 0, s[10:11]
	global_load_dwordx4 v[50:53], v[48:49], off nt
	v_add_co_u32_e32 v110, vcc, s27, v48
	s_nop 1
	v_addc_co_u32_e32 v111, vcc, 0, v49, vcc
	global_load_dword v112, v[110:111], off nt
	v_add_co_u32_e32 v110, vcc, s25, v48
	s_nop 1
	v_addc_co_u32_e32 v111, vcc, 0, v49, vcc
	global_load_dword v112, v[110:111], off nt
	v_add_co_u32_e32 v110, vcc, s38, v48
	s_nop 1
	v_addc_co_u32_e32 v111, vcc, 0, v49, vcc
	global_load_dword v112, v[110:111], off nt
	v_add_co_u32_e32 v110, vcc, s39, v48
	s_nop 1
	v_addc_co_u32_e32 v111, vcc, 0, v49, vcc
	global_load_dword v112, v[110:111], off nt
	v_add_co_u32_e32 v110, vcc, s78, v48
	s_nop 1
	v_addc_co_u32_e32 v111, vcc, 0, v49, vcc
	global_load_dword v112, v[110:111], off nt
	v_add_co_u32_e32 v110, vcc, s79, v48
	s_nop 1
	v_addc_co_u32_e32 v111, vcc, 0, v49, vcc
	global_load_dword v112, v[110:111], off nt
	v_add_co_u32_e32 v110, vcc, s68, v48
	s_nop 1
	v_addc_co_u32_e32 v111, vcc, 0, v49, vcc
	global_load_dword v112, v[110:111], off nt
	ds_read_b128 v[70:73], v68
	ds_read_b128 v[38:41], v68 offset:16
	ds_read_b128 v[54:57], v68 offset:4096
	ds_read_b128 v[78:81], v68 offset:12288
	ds_read_b128 v[82:85], v68 offset:20480
	s_waitcnt lgkmcnt(0)
	v_mov_b32_e32 v74, v70
	ds_read_b128 v[90:93], v68 offset:28672
	v_mov_b32_e32 v75, v54
	s_add_u32 s10, s10, 0x30000
	s_addc_u32 s11, s11, 0
	s_cmp_lg_u32 s10, 0x180000
	s_waitcnt lgkmcnt(0)
	v_mov_b32_e32 v104, v90
	ds_read_b128 v[94:97], v68 offset:32768
	ds_read_b128 v[86:89], v68 offset:24576
	s_waitcnt lgkmcnt(0)
	v_mov_b32_e32 v105, v94
	s_waitcnt vmcnt(0)
	v_pk_fma_f32 v[98:99], v[50:51], v[74:75], v[26:27] op_sel_hi:[0,1,1]
	v_pk_fma_f32 v[100:101], v[52:53], v[74:75], v[4:5] op_sel_hi:[0,1,1]
	ds_read_b128 v[74:77], v68 offset:8192
	v_mov_b32_e32 v4, v54
	v_mov_b32_e32 v54, v53
	v_pk_fma_f32 v[16:17], v[54:55], v[104:105], v[16:17] op_sel_hi:[0,1,1]
	s_waitcnt lgkmcnt(0)
	v_mov_b32_e32 v5, v74
	v_pk_fma_f32 v[8:9], v[50:51], v[4:5], v[8:9] op_sel:[1,0,0]
	v_pk_fma_f32 v[34:35], v[54:55], v[4:5], v[34:35] op_sel_hi:[0,1,1]
	v_mov_b32_e32 v4, v74
	v_mov_b32_e32 v5, v78
	v_pk_fma_f32 v[102:103], v[50:51], v[4:5], v[28:29] op_sel_hi:[0,1,1]
	ds_read_b128 v[26:29], v68 offset:16384
	v_pk_fma_f32 v[30:31], v[52:53], v[4:5], v[30:31] op_sel_hi:[0,1,1]
	v_mov_b32_e32 v4, v78
	v_mov_b32_e32 v74, v55
	v_mov_b32_e32 v78, v75
	s_waitcnt lgkmcnt(0)
	v_mov_b32_e32 v5, v26
	v_pk_fma_f32 v[22:23], v[50:51], v[4:5], v[22:23] op_sel:[1,0,0]
	v_pk_fma_f32 v[36:37], v[54:55], v[4:5], v[36:37] op_sel_hi:[0,1,1]
	v_mov_b32_e32 v4, v26
	v_mov_b32_e32 v5, v82
	v_pk_fma_f32 v[10:11], v[50:51], v[4:5], v[10:11] op_sel_hi:[0,1,1]
	v_pk_fma_f32 v[32:33], v[52:53], v[4:5], v[32:33] op_sel_hi:[0,1,1]
	v_mov_b32_e32 v4, v82
	v_mov_b32_e32 v5, v86
	v_pk_fma_f32 v[24:25], v[50:51], v[4:5], v[24:25] op_sel:[1,0,0]
	v_pk_fma_f32 v[14:15], v[54:55], v[4:5], v[14:15] op_sel_hi:[0,1,1]
	v_mov_b32_e32 v4, v86
	v_mov_b32_e32 v5, v90
	v_pk_fma_f32 v[12:13], v[50:51], v[4:5], v[12:13] op_sel_hi:[0,1,1]
	v_pk_fma_f32 v[18:19], v[52:53], v[4:5], v[18:19] op_sel_hi:[0,1,1]
	v_mov_b32_e32 v4, v94
	v_mov_b32_e32 v5, v70
	v_pk_fma_f32 v[6:7], v[50:51], v[4:5], v[6:7]
	v_pk_fma_f32 v[50:51], v[50:51], v[104:105], v[2:3] op_sel:[1,0,0]
	v_add_co_u32_e32 v2, vcc, s27, v48
	v_pk_fma_f32 v[20:21], v[52:53], v[4:5], v[20:21]
	s_nop 0
	v_addc_co_u32_e32 v3, vcc, 0, v49, vcc
	global_load_dwordx4 v[2:5], v[2:3], off nt
	v_mov_b32_e32 v54, v71
	v_mov_b32_e32 v26, v79
	v_mov_b32_e32 v82, v27
	v_mov_b32_e32 v86, v83
	v_mov_b32_e32 v90, v87
	v_mov_b32_e32 v70, v95
	v_mov_b32_e32 v94, v91
	s_waitcnt vmcnt(0)
	v_pk_fma_f32 v[52:53], v[2:3], v[54:55], v[98:99] op_sel_hi:[0,1,1]
	v_pk_fma_f32 v[98:99], v[4:5], v[54:55], v[100:101] op_sel_hi:[0,1,1]
	v_mov_b32_e32 v54, v5
	v_pk_fma_f32 v[8:9], v[2:3], v[74:75], v[8:9] op_sel:[1,0,0]
	v_pk_fma_f32 v[34:35], v[54:55], v[74:75], v[34:35] op_sel_hi:[0,1,1]
	v_pk_fma_f32 v[74:75], v[2:3], v[78:79], v[102:103] op_sel_hi:[0,1,1]
	v_pk_fma_f32 v[22:23], v[2:3], v[26:27], v[22:23] op_sel:[1,0,0]
	v_pk_fma_f32 v[36:37], v[54:55], v[26:27], v[36:37] op_sel_hi:[0,1,1]
	v_pk_fma_f32 v[10:11], v[2:3], v[82:83], v[10:11] op_sel_hi:[0,1,1]
	v_pk_fma_f32 v[26:27], v[4:5], v[82:83], v[32:33] op_sel_hi:[0,1,1]
	v_pk_fma_f32 v[24:25], v[2:3], v[86:87], v[24:25] op_sel:[1,0,0]
	v_pk_fma_f32 v[12:13], v[2:3], v[90:91], v[12:13] op_sel_hi:[0,1,1]
	v_pk_fma_f32 v[6:7], v[2:3], v[70:71], v[6:7]
	v_pk_fma_f32 v[32:33], v[2:3], v[94:95], v[50:51] op_sel:[1,0,0]
	v_add_co_u32_e32 v2, vcc, s25, v48
	v_pk_fma_f32 v[30:31], v[4:5], v[78:79], v[30:31] op_sel_hi:[0,1,1]
	s_nop 0
	v_addc_co_u32_e32 v3, vcc, 0, v49, vcc
	v_pk_fma_f32 v[18:19], v[4:5], v[90:91], v[18:19] op_sel_hi:[0,1,1]
	v_pk_fma_f32 v[20:21], v[4:5], v[70:71], v[20:21]
	global_load_dwordx4 v[2:5], v[2:3], off nt
	v_pk_fma_f32 v[14:15], v[54:55], v[86:87], v[14:15] op_sel_hi:[0,1,1]
	v_pk_fma_f32 v[16:17], v[54:55], v[94:95], v[16:17] op_sel_hi:[0,1,1]
	v_mov_b32_e32 v51, v56
	v_mov_b32_e32 v54, v56
	v_mov_b32_e32 v55, v76
	v_mov_b32_e32 v50, v72
	s_waitcnt vmcnt(0)
; DI void phase_ada(const float* c_in, const float* cctx_in, const float* w_ada, const float* b_ada, unsigned char* ws, unsigned char* lds) {
;     ...
;         for (int k = kg * 64; k < kg * 64 + 64; ++k) {
;             const f32x4 w = __builtin_nontemporal_load((const f32x4*)(W + (size_t)k * 6144));
; #pragma unroll
;             for (int r = 0; r < 9; ++r) { const float sv = sc[r * 1024 + k]; acc[r][0] += sv * w[0]; acc[r][1] += sv * w[1]; acc[r][2] += sv * w[2]; acc[r][3] += sv * w[3]; }
	v_mov_b32_e32 v56, v5
	v_pk_fma_f32 v[8:9], v[2:3], v[54:55], v[8:9] op_sel:[1,0,0]
	v_pk_fma_f32 v[34:35], v[56:57], v[54:55], v[34:35] op_sel_hi:[0,1,1]
	v_mov_b32_e32 v54, v76
	v_mov_b32_e32 v55, v80
	v_pk_fma_f32 v[70:71], v[2:3], v[54:55], v[74:75] op_sel_hi:[0,1,1]
	v_pk_fma_f32 v[30:31], v[4:5], v[54:55], v[30:31] op_sel_hi:[0,1,1]
	v_mov_b32_e32 v54, v80
	v_mov_b32_e32 v55, v28
	v_pk_fma_f32 v[22:23], v[2:3], v[54:55], v[22:23] op_sel:[1,0,0]
	v_pk_fma_f32 v[36:37], v[56:57], v[54:55], v[36:37] op_sel_hi:[0,1,1]
	v_mov_b32_e32 v54, v28
	v_mov_b32_e32 v55, v84
	v_pk_fma_f32 v[74:75], v[2:3], v[54:55], v[10:11] op_sel_hi:[0,1,1]
	v_mov_b32_e32 v10, v84
	v_mov_b32_e32 v11, v88
	v_pk_fma_f32 v[24:25], v[2:3], v[10:11], v[24:25] op_sel:[1,0,0]
	v_pk_fma_f32 v[14:15], v[56:57], v[10:11], v[14:15] op_sel_hi:[0,1,1]
	v_mov_b32_e32 v10, v88
	v_mov_b32_e32 v11, v92
	v_pk_fma_f32 v[78:79], v[2:3], v[10:11], v[12:13] op_sel_hi:[0,1,1]
	v_pk_fma_f32 v[18:19], v[4:5], v[10:11], v[18:19] op_sel_hi:[0,1,1]
	v_mov_b32_e32 v10, v96
	v_mov_b32_e32 v11, v72
	v_mov_b32_e32 v12, v92
	v_mov_b32_e32 v13, v96
	v_pk_fma_f32 v[52:53], v[2:3], v[50:51], v[52:53] op_sel_hi:[0,1,1]
	v_pk_fma_f32 v[6:7], v[2:3], v[10:11], v[6:7]
	v_pk_fma_f32 v[82:83], v[2:3], v[12:13], v[32:33] op_sel:[1,0,0]
	v_add_co_u32_e32 v2, vcc, s38, v48
	v_pk_fma_f32 v[50:51], v[4:5], v[50:51], v[98:99] op_sel_hi:[0,1,1]
	s_nop 0
	v_addc_co_u32_e32 v3, vcc, 0, v49, vcc
	v_pk_fma_f32 v[26:27], v[4:5], v[54:55], v[26:27] op_sel_hi:[0,1,1]
	v_pk_fma_f32 v[86:87], v[4:5], v[10:11], v[20:21]
	global_load_dwordx4 v[2:5], v[2:3], off nt
	v_mov_b32_e32 v76, v57
	v_pk_fma_f32 v[90:91], v[56:57], v[12:13], v[16:17] op_sel_hi:[0,1,1]
	v_mov_b32_e32 v56, v73
	v_mov_b32_e32 v80, v77
	v_mov_b32_e32 v28, v81
	v_mov_b32_e32 v84, v29
	v_mov_b32_e32 v88, v85
	v_mov_b32_e32 v92, v89
	v_mov_b32_e32 v72, v97
	v_mov_b32_e32 v96, v93
	v_mov_b32_e32 v99, v38
	s_waitcnt vmcnt(0)
	v_pk_fma_f32 v[54:55], v[2:3], v[76:77], v[8:9] op_sel:[1,0,0]
	v_mov_b32_e32 v8, v5
	v_pk_fma_f32 v[10:11], v[2:3], v[56:57], v[52:53] op_sel_hi:[0,1,1]
	v_pk_fma_f32 v[12:13], v[4:5], v[56:57], v[50:51] op_sel_hi:[0,1,1]
	v_pk_fma_f32 v[56:57], v[8:9], v[76:77], v[34:35] op_sel_hi:[0,1,1]
	v_pk_fma_f32 v[50:51], v[2:3], v[80:81], v[70:71] op_sel_hi:[0,1,1]
	v_pk_fma_f32 v[52:53], v[4:5], v[80:81], v[30:31] op_sel_hi:[0,1,1]
	v_pk_fma_f32 v[34:35], v[2:3], v[28:29], v[22:23] op_sel:[1,0,0]
	v_pk_fma_f32 v[36:37], v[8:9], v[28:29], v[36:37] op_sel_hi:[0,1,1]
	v_pk_fma_f32 v[30:31], v[2:3], v[84:85], v[74:75] op_sel_hi:[0,1,1]
	v_pk_fma_f32 v[32:33], v[4:5], v[84:85], v[26:27] op_sel_hi:[0,1,1]
	v_pk_fma_f32 v[26:27], v[2:3], v[88:89], v[24:25] op_sel:[1,0,0]
	v_pk_fma_f32 v[28:29], v[8:9], v[88:89], v[14:15] op_sel_hi:[0,1,1]
	v_pk_fma_f32 v[22:23], v[2:3], v[92:93], v[78:79] op_sel_hi:[0,1,1]
	v_pk_fma_f32 v[20:21], v[2:3], v[72:73], v[6:7]
	v_pk_fma_f32 v[14:15], v[2:3], v[96:97], v[82:83] op_sel:[1,0,0]
	v_add_co_u32_e32 v2, vcc, s39, v48
	v_pk_fma_f32 v[24:25], v[4:5], v[92:93], v[18:19] op_sel_hi:[0,1,1]
	s_nop 0
	v_addc_co_u32_e32 v3, vcc, 0, v49, vcc
	v_pk_fma_f32 v[16:17], v[4:5], v[72:73], v[86:87]
	global_load_dwordx4 v[2:5], v[2:3], off nt
	v_pk_fma_f32 v[18:19], v[8:9], v[96:97], v[90:91] op_sel_hi:[0,1,1]
	ds_read_b128 v[6:9], v68 offset:4112
	v_mov_b32_e32 v70, v38
	s_waitcnt lgkmcnt(0)
	v_mov_b32_e32 v71, v6
	s_waitcnt vmcnt(0)
	v_pk_fma_f32 v[86:87], v[2:3], v[70:71], v[10:11] op_sel_hi:[0,1,1]
	v_pk_fma_f32 v[88:89], v[4:5], v[70:71], v[12:13] op_sel_hi:[0,1,1]
	ds_read_b128 v[10:13], v68 offset:8208
	v_mov_b32_e32 v70, v6
	v_mov_b32_e32 v6, v5
	s_waitcnt lgkmcnt(0)
	v_mov_b32_e32 v71, v10
	v_pk_fma_f32 v[90:91], v[2:3], v[70:71], v[54:55] op_sel:[1,0,0]
	v_pk_fma_f32 v[92:93], v[6:7], v[70:71], v[56:57] op_sel_hi:[0,1,1]
	ds_read_b128 v[54:57], v68 offset:12304
	v_mov_b32_e32 v70, v10
	v_mov_b32_e32 v10, v7
	s_waitcnt lgkmcnt(0)
	v_mov_b32_e32 v71, v54
	v_pk_fma_f32 v[94:95], v[2:3], v[70:71], v[50:51] op_sel_hi:[0,1,1]
	v_pk_fma_f32 v[96:97], v[4:5], v[70:71], v[52:53] op_sel_hi:[0,1,1]
	ds_read_b128 v[50:53], v68 offset:16400
	v_mov_b32_e32 v70, v54
	v_mov_b32_e32 v54, v11
	s_waitcnt lgkmcnt(0)
	v_mov_b32_e32 v71, v50
	v_pk_fma_f32 v[34:35], v[2:3], v[70:71], v[34:35] op_sel:[1,0,0]
	v_pk_fma_f32 v[36:37], v[6:7], v[70:71], v[36:37] op_sel_hi:[0,1,1]
	ds_read_b128 v[70:73], v68 offset:20496
	v_mov_b32_e32 v74, v50
	v_mov_b32_e32 v50, v55
	s_waitcnt lgkmcnt(0)
	v_mov_b32_e32 v75, v70
	v_pk_fma_f32 v[30:31], v[2:3], v[74:75], v[30:31] op_sel_hi:[0,1,1]
	v_pk_fma_f32 v[32:33], v[4:5], v[74:75], v[32:33] op_sel_hi:[0,1,1]
	ds_read_b128 v[74:77], v68 offset:24592
	v_mov_b32_e32 v78, v70
	v_mov_b32_e32 v70, v51
	s_waitcnt lgkmcnt(0)
	v_mov_b32_e32 v79, v74
	v_pk_fma_f32 v[26:27], v[2:3], v[78:79], v[26:27] op_sel:[1,0,0]
	v_pk_fma_f32 v[28:29], v[6:7], v[78:79], v[28:29] op_sel_hi:[0,1,1]
	ds_read_b128 v[78:81], v68 offset:28688
	v_mov_b32_e32 v82, v74
	v_mov_b32_e32 v74, v71
	s_waitcnt lgkmcnt(0)
	v_mov_b32_e32 v83, v78
	v_pk_fma_f32 v[22:23], v[2:3], v[82:83], v[22:23] op_sel_hi:[0,1,1]
	v_pk_fma_f32 v[24:25], v[4:5], v[82:83], v[24:25] op_sel_hi:[0,1,1]
	ds_read_b128 v[82:85], v68 offset:32784
	v_mov_b32_e32 v100, v78
	v_mov_b32_e32 v78, v75
	v_add_u32_e32 v68, 32, v68
	s_waitcnt lgkmcnt(0)
	v_mov_b32_e32 v98, v82
	v_mov_b32_e32 v101, v82
	v_pk_fma_f32 v[20:21], v[2:3], v[98:99], v[20:21]
	v_pk_fma_f32 v[14:15], v[2:3], v[100:101], v[14:15] op_sel:[1,0,0]
	v_add_co_u32_e32 v2, vcc, s78, v48
	v_pk_fma_f32 v[16:17], v[4:5], v[98:99], v[16:17]
	s_nop 0
	v_addc_co_u32_e32 v3, vcc, 0, v49, vcc
	global_load_dwordx4 v[2:5], v[2:3], off nt
	v_pk_fma_f32 v[18:19], v[6:7], v[100:101], v[18:19] op_sel_hi:[0,1,1]
	v_mov_b32_e32 v6, v39
	v_mov_b32_e32 v38, v83
	v_mov_b32_e32 v82, v79
	s_waitcnt vmcnt(0)
; DI void phase_ada(const float* c_in, const float* cctx_in, const float* w_ada, const float* b_ada, unsigned char* ws, unsigned char* lds) {
;     ...
;         for (int k = kg * 64; k < kg * 64 + 64; ++k) {
;             const f32x4 w = __builtin_nontemporal_load((const f32x4*)(W + (size_t)k * 6144));
; #pragma unroll
;             for (int r = 0; r < 9; ++r) { const float sv = sc[r * 1024 + k]; acc[r][0] += sv * w[0]; acc[r][1] += sv * w[1]; acc[r][2] += sv * w[2]; acc[r][3] += sv * w[3]; }
;         }
; #pragma unroll
;         for (int r = 0; r < 9; ++r)
; #pragma unroll
;             for (int j = 0; j < 4; ++j) red[(kg * 128 + c4 + j) * 9 + r] = acc[r][j];
	v_pk_fma_f32 v[86:87], v[2:3], v[6:7], v[86:87] op_sel_hi:[0,1,1]
	v_pk_fma_f32 v[88:89], v[4:5], v[6:7], v[88:89] op_sel_hi:[0,1,1]
	v_pk_fma_f32 v[6:7], v[2:3], v[10:11], v[90:91] op_sel:[1,0,0]
	v_mov_b32_e32 v90, v5
	v_pk_fma_f32 v[92:93], v[90:91], v[10:11], v[92:93] op_sel_hi:[0,1,1]
	v_pk_fma_f32 v[10:11], v[2:3], v[54:55], v[94:95] op_sel_hi:[0,1,1]
	v_pk_fma_f32 v[34:35], v[2:3], v[50:51], v[34:35] op_sel:[1,0,0]
	v_pk_fma_f32 v[30:31], v[2:3], v[70:71], v[30:31] op_sel_hi:[0,1,1]
	v_pk_fma_f32 v[26:27], v[2:3], v[74:75], v[26:27] op_sel:[1,0,0]
	v_pk_fma_f32 v[22:23], v[2:3], v[78:79], v[22:23] op_sel_hi:[0,1,1]
	v_pk_fma_f32 v[20:21], v[2:3], v[38:39], v[20:21]
	v_pk_fma_f32 v[14:15], v[2:3], v[82:83], v[14:15] op_sel:[1,0,0]
	v_add_co_u32_e32 v2, vcc, s79, v48
	v_pk_fma_f32 v[94:95], v[4:5], v[54:55], v[96:97] op_sel_hi:[0,1,1]
	s_nop 0
	v_addc_co_u32_e32 v3, vcc, 0, v49, vcc
	v_pk_fma_f32 v[32:33], v[4:5], v[70:71], v[32:33] op_sel_hi:[0,1,1]
	v_pk_fma_f32 v[24:25], v[4:5], v[78:79], v[24:25] op_sel_hi:[0,1,1]
	v_pk_fma_f32 v[16:17], v[4:5], v[38:39], v[16:17]
	global_load_dwordx4 v[2:5], v[2:3], off nt
	v_pk_fma_f32 v[36:37], v[90:91], v[50:51], v[36:37] op_sel_hi:[0,1,1]
	v_mov_b32_e32 v39, v8
	v_mov_b32_e32 v50, v8
	v_mov_b32_e32 v51, v12
	v_pk_fma_f32 v[28:29], v[90:91], v[74:75], v[28:29] op_sel_hi:[0,1,1]
	v_pk_fma_f32 v[18:19], v[90:91], v[82:83], v[18:19] op_sel_hi:[0,1,1]
	v_mov_b32_e32 v38, v40
	s_waitcnt vmcnt(0)
	v_mov_b32_e32 v8, v5
	v_pk_fma_f32 v[6:7], v[2:3], v[50:51], v[6:7] op_sel:[1,0,0]
	v_pk_fma_f32 v[70:71], v[8:9], v[50:51], v[92:93] op_sel_hi:[0,1,1]
	v_mov_b32_e32 v50, v12
	v_mov_b32_e32 v51, v56
	v_pk_fma_f32 v[10:11], v[2:3], v[50:51], v[10:11] op_sel_hi:[0,1,1]
	v_pk_fma_f32 v[74:75], v[4:5], v[50:51], v[94:95] op_sel_hi:[0,1,1]
	v_mov_b32_e32 v50, v56
	v_mov_b32_e32 v51, v52
	v_pk_fma_f32 v[78:79], v[2:3], v[50:51], v[34:35] op_sel:[1,0,0]
	v_mov_b32_e32 v34, v52
	v_mov_b32_e32 v35, v72
	v_pk_fma_f32 v[82:83], v[2:3], v[34:35], v[30:31] op_sel_hi:[0,1,1]
	v_mov_b32_e32 v30, v72
	v_mov_b32_e32 v31, v76
	v_pk_fma_f32 v[54:55], v[2:3], v[38:39], v[86:87] op_sel_hi:[0,1,1]
	v_pk_fma_f32 v[86:87], v[2:3], v[30:31], v[26:27] op_sel:[1,0,0]
	v_mov_b32_e32 v26, v76
	v_mov_b32_e32 v27, v80
	v_pk_fma_f32 v[90:91], v[2:3], v[26:27], v[22:23] op_sel_hi:[0,1,1]
	v_mov_b32_e32 v22, v84
	v_mov_b32_e32 v23, v40
	v_pk_fma_f32 v[38:39], v[4:5], v[38:39], v[88:89] op_sel_hi:[0,1,1]
	v_pk_fma_f32 v[32:33], v[4:5], v[34:35], v[32:33] op_sel_hi:[0,1,1]
	v_pk_fma_f32 v[92:93], v[4:5], v[26:27], v[24:25] op_sel_hi:[0,1,1]
	v_pk_fma_f32 v[16:17], v[4:5], v[22:23], v[16:17]
	v_add_co_u32_e32 v4, vcc, s68, v48
	v_pk_fma_f32 v[36:37], v[8:9], v[50:51], v[36:37] op_sel_hi:[0,1,1]
	s_nop 0
	v_addc_co_u32_e32 v5, vcc, 0, v49, vcc
	global_load_dwordx4 v[48:51], v[4:5], off nt
	v_mov_b32_e32 v24, v80
	v_mov_b32_e32 v25, v84
	v_pk_fma_f32 v[88:89], v[8:9], v[30:31], v[28:29] op_sel_hi:[0,1,1]
	v_pk_fma_f32 v[94:95], v[8:9], v[24:25], v[18:19] op_sel_hi:[0,1,1]
	v_mov_b32_e32 v8, v41
	v_pk_fma_f32 v[20:21], v[2:3], v[22:23], v[20:21]
	v_pk_fma_f32 v[2:3], v[2:3], v[24:25], v[14:15] op_sel:[1,0,0]
	v_mov_b32_e32 v12, v9
	v_mov_b32_e32 v56, v13
	v_mov_b32_e32 v52, v57
	v_mov_b32_e32 v72, v53
	v_mov_b32_e32 v76, v73
	v_mov_b32_e32 v80, v77
	v_mov_b32_e32 v40, v85
	v_mov_b32_e32 v84, v81
	s_waitcnt vmcnt(0)
	v_pk_fma_f32 v[4:5], v[50:51], v[8:9], v[38:39] op_sel_hi:[0,1,1]
	v_mov_b32_e32 v38, v51
	v_pk_fma_f32 v[26:27], v[48:49], v[8:9], v[54:55] op_sel_hi:[0,1,1]
	v_pk_fma_f32 v[8:9], v[48:49], v[12:13], v[6:7] op_sel:[1,0,0]
	v_pk_fma_f32 v[34:35], v[38:39], v[12:13], v[70:71] op_sel_hi:[0,1,1]
	v_pk_fma_f32 v[28:29], v[48:49], v[56:57], v[10:11] op_sel_hi:[0,1,1]
	v_pk_fma_f32 v[30:31], v[50:51], v[56:57], v[74:75] op_sel_hi:[0,1,1]
	v_pk_fma_f32 v[22:23], v[48:49], v[52:53], v[78:79] op_sel:[1,0,0]
	v_pk_fma_f32 v[36:37], v[38:39], v[52:53], v[36:37] op_sel_hi:[0,1,1]
	v_pk_fma_f32 v[10:11], v[48:49], v[72:73], v[82:83] op_sel_hi:[0,1,1]
	v_pk_fma_f32 v[32:33], v[50:51], v[72:73], v[32:33] op_sel_hi:[0,1,1]
	v_pk_fma_f32 v[24:25], v[48:49], v[76:77], v[86:87] op_sel:[1,0,0]
	v_pk_fma_f32 v[14:15], v[38:39], v[76:77], v[88:89] op_sel_hi:[0,1,1]
	v_pk_fma_f32 v[12:13], v[48:49], v[80:81], v[90:91] op_sel_hi:[0,1,1]
	v_pk_fma_f32 v[18:19], v[50:51], v[80:81], v[92:93] op_sel_hi:[0,1,1]
	v_pk_fma_f32 v[6:7], v[48:49], v[40:41], v[20:21]
	v_pk_fma_f32 v[2:3], v[48:49], v[84:85], v[2:3] op_sel:[1,0,0]
	v_pk_fma_f32 v[20:21], v[50:51], v[40:41], v[16:17]
	v_pk_fma_f32 v[16:17], v[38:39], v[84:85], v[94:95] op_sel_hi:[0,1,1]
	s_cbranch_scc1 .LBB0_182
	ds_write_b128 v58, v[26:29] offset:36864
	ds_write_b128 v58, v[34:37] offset:36976
	ds_write_b128 v58, v[30:33] offset:36944
	ds_write_b128 v58, v[22:25] offset:36912
	ds_write_b128 v58, v[10:13] offset:36880
	ds_write_b128 v58, v[6:9] offset:36896
	ds_write_b128 v58, v[2:5] offset:36928
	ds_write_b128 v58, v[18:21] offset:36960
	ds_write_b128 v58, v[14:17] offset:36992
	s_waitcnt lgkmcnt(0)
	s_barrier
	s_and_saveexec_b64 s[10:11], s[40:41]
	s_cbranch_execz .LBB0_180
; DI void phase_ada(const float* c_in, const float* cctx_in, const float* w_ada, const float* b_ada, unsigned char* ws, unsigned char* lds) {
;     ...
;         if (tid < 128) {
;             const int col = cgp * 128 + tid;
;             const float bb = b_ada[l * 6144 + col];
; #pragma unroll
;             for (int r = 0; r < 9; ++r) {
;                 float s = 0.f;
; #pragma unroll
;                 for (int g = 0; g < 16; ++g) s += red[(g * 128 + tid) * 9 + r];
;                 modt[((size_t)l * 9 + r) * 6144 + col] = s + bb;
;             }
	v_add_u32_e32 v2, s8, v42
	s_mul_i32 s4, s3, 0x1800
	v_add_u32_e32 v4, s4, v2
	v_ashrrev_i32_e32 v5, 31, v4
	v_lshl_add_u64 v[4:5], v[4:5], 2, s[6:7]
	global_load_dword v6, v[4:5], off
	ds_read_b32 v4, v0 offset:36864
	ds_read_b32 v5, v0 offset:41472
	v_ashrrev_i32_e32 v3, 31, v2
	s_mul_i32 s3, s3, 9
	v_lshl_add_u64 v[2:3], v[2:3], 2, s[12:13]
	s_waitcnt lgkmcnt(1)
	v_add_f32_e32 v4, 0, v4
	s_waitcnt lgkmcnt(0)
	v_add_f32_e32 v4, v4, v5
	ds_read_b32 v5, v0 offset:46080
	v_mad_i64_i32 v[2:3], s[4:5], s3, v184, v[2:3]
	s_waitcnt lgkmcnt(0)
	v_add_f32_e32 v4, v4, v5
	ds_read_b32 v5, v0 offset:50688
	s_waitcnt lgkmcnt(0)
	v_add_f32_e32 v4, v4, v5
	ds_read_b32 v5, v0 offset:55296
	s_waitcnt lgkmcnt(0)
	v_add_f32_e32 v4, v4, v5
	ds_read_b32 v5, v0 offset:59904
	s_waitcnt lgkmcnt(0)
	v_add_f32_e32 v4, v4, v5
	ds_read_b32 v5, v0 offset:64512
	s_waitcnt lgkmcnt(0)
	v_add_f32_e32 v4, v4, v5
	ds_read_b32 v5, v59 offset:36864
	s_waitcnt lgkmcnt(0)
	v_add_f32_e32 v4, v4, v5
	ds_read_b32 v5, v60 offset:36864
	s_waitcnt lgkmcnt(0)
	v_add_f32_e32 v4, v4, v5
	ds_read_b32 v5, v61 offset:36864
	s_waitcnt lgkmcnt(0)
	v_add_f32_e32 v4, v4, v5
	ds_read_b32 v5, v62 offset:36864
	s_waitcnt lgkmcnt(0)
	v_add_f32_e32 v4, v4, v5
	ds_read_b32 v5, v63 offset:36864
	s_waitcnt lgkmcnt(0)
	v_add_f32_e32 v4, v4, v5
	ds_read_b32 v5, v64 offset:36864
	s_waitcnt lgkmcnt(0)
	v_add_f32_e32 v4, v4, v5
	ds_read_b32 v5, v65 offset:36864
	s_waitcnt lgkmcnt(0)
	v_add_f32_e32 v4, v4, v5
	ds_read_b32 v5, v66 offset:36864
	s_waitcnt lgkmcnt(0)
	v_add_f32_e32 v4, v4, v5
	ds_read_b32 v5, v67 offset:36864
	s_waitcnt lgkmcnt(0)
	v_add_f32_e32 v4, v4, v5
	s_waitcnt vmcnt(0)
	v_add_f32_e32 v4, v6, v4
	flat_store_dword v[2:3], v4
	ds_read_b32 v4, v0 offset:36868
	ds_read_b32 v5, v0 offset:41476
	s_waitcnt lgkmcnt(0)
	v_add_f32_e32 v4, 0, v4
	v_add_f32_e32 v4, v4, v5
	ds_read_b32 v5, v0 offset:46084
	s_waitcnt lgkmcnt(0)
	v_add_f32_e32 v4, v4, v5
	ds_read_b32 v5, v0 offset:50692
	s_waitcnt lgkmcnt(0)
	v_add_f32_e32 v4, v4, v5
	ds_read_b32 v5, v0 offset:55300
	s_waitcnt lgkmcnt(0)
	v_add_f32_e32 v4, v4, v5
	ds_read_b32 v5, v0 offset:59908
	s_waitcnt lgkmcnt(0)
	v_add_f32_e32 v4, v4, v5
	ds_read_b32 v5, v0 offset:64516
	s_waitcnt lgkmcnt(0)
	v_add_f32_e32 v4, v4, v5
	ds_read_b32 v5, v59 offset:36868
	s_waitcnt lgkmcnt(0)
	v_add_f32_e32 v4, v4, v5
	ds_read_b32 v5, v60 offset:36868
	s_waitcnt lgkmcnt(0)
	v_add_f32_e32 v4, v4, v5
	ds_read_b32 v5, v61 offset:36868
	s_waitcnt lgkmcnt(0)
	v_add_f32_e32 v4, v4, v5
	ds_read_b32 v5, v62 offset:36868
	s_waitcnt lgkmcnt(0)
	v_add_f32_e32 v4, v4, v5
	ds_read_b32 v5, v63 offset:36868
	s_waitcnt lgkmcnt(0)
	v_add_f32_e32 v4, v4, v5
	ds_read_b32 v5, v64 offset:36868
	s_waitcnt lgkmcnt(0)
	v_add_f32_e32 v4, v4, v5
	ds_read_b32 v5, v65 offset:36868
	s_waitcnt lgkmcnt(0)
	v_add_f32_e32 v4, v4, v5
	ds_read_b32 v5, v66 offset:36868
	s_waitcnt lgkmcnt(0)
	v_add_f32_e32 v4, v4, v5
	ds_read_b32 v5, v67 offset:36868
	s_waitcnt lgkmcnt(0)
	v_add_f32_e32 v4, v4, v5
	v_add_f32_e32 v7, v6, v4
	v_add_co_u32_e32 v4, vcc, s27, v2
	s_nop 1
	v_addc_co_u32_e32 v5, vcc, 0, v3, vcc
	flat_store_dword v[4:5], v7
	ds_read_b32 v4, v0 offset:36872
	ds_read_b32 v5, v0 offset:41480
	s_waitcnt lgkmcnt(0)
	v_add_f32_e32 v4, 0, v4
	v_add_f32_e32 v4, v4, v5
	ds_read_b32 v5, v0 offset:46088
	s_waitcnt lgkmcnt(0)
	v_add_f32_e32 v4, v4, v5
	ds_read_b32 v5, v0 offset:50696
	s_waitcnt lgkmcnt(0)
	v_add_f32_e32 v4, v4, v5
	ds_read_b32 v5, v0 offset:55304
	s_waitcnt lgkmcnt(0)
	v_add_f32_e32 v4, v4, v5
	ds_read_b32 v5, v0 offset:59912
	s_waitcnt lgkmcnt(0)
	v_add_f32_e32 v4, v4, v5
	ds_read_b32 v5, v0 offset:64520
	s_waitcnt lgkmcnt(0)
	v_add_f32_e32 v4, v4, v5
	ds_read_b32 v5, v59 offset:36872
	s_waitcnt lgkmcnt(0)
	v_add_f32_e32 v4, v4, v5
	ds_read_b32 v5, v60 offset:36872
	s_waitcnt lgkmcnt(0)
	v_add_f32_e32 v4, v4, v5
	ds_read_b32 v5, v61 offset:36872
	s_waitcnt lgkmcnt(0)
	v_add_f32_e32 v4, v4, v5
	ds_read_b32 v5, v62 offset:36872
	s_waitcnt lgkmcnt(0)
	v_add_f32_e32 v4, v4, v5
	ds_read_b32 v5, v63 offset:36872
	s_waitcnt lgkmcnt(0)
	v_add_f32_e32 v4, v4, v5
	ds_read_b32 v5, v64 offset:36872
	s_waitcnt lgkmcnt(0)
	v_add_f32_e32 v4, v4, v5
	ds_read_b32 v5, v65 offset:36872
	s_waitcnt lgkmcnt(0)
	v_add_f32_e32 v4, v4, v5
	ds_read_b32 v5, v66 offset:36872
	s_waitcnt lgkmcnt(0)
	v_add_f32_e32 v4, v4, v5
	ds_read_b32 v5, v67 offset:36872
	s_waitcnt lgkmcnt(0)
	v_add_f32_e32 v4, v4, v5
	v_add_f32_e32 v7, v6, v4
	v_add_co_u32_e32 v4, vcc, s25, v2
	s_nop 1
	v_addc_co_u32_e32 v5, vcc, 0, v3, vcc
	flat_store_dword v[4:5], v7
	ds_read_b32 v4, v0 offset:36876
	ds_read_b32 v5, v0 offset:41484
	s_waitcnt lgkmcnt(0)
	v_add_f32_e32 v4, 0, v4
	v_add_f32_e32 v4, v4, v5
	ds_read_b32 v5, v0 offset:46092
	s_waitcnt lgkmcnt(0)
	v_add_f32_e32 v4, v4, v5
	ds_read_b32 v5, v0 offset:50700
	s_waitcnt lgkmcnt(0)
	v_add_f32_e32 v4, v4, v5
	ds_read_b32 v5, v0 offset:55308
	s_waitcnt lgkmcnt(0)
	v_add_f32_e32 v4, v4, v5
	ds_read_b32 v5, v0 offset:59916
	s_waitcnt lgkmcnt(0)
	v_add_f32_e32 v4, v4, v5
	ds_read_b32 v5, v0 offset:64524
	s_waitcnt lgkmcnt(0)
	v_add_f32_e32 v4, v4, v5
	ds_read_b32 v5, v59 offset:36876
	s_waitcnt lgkmcnt(0)
	v_add_f32_e32 v4, v4, v5
	ds_read_b32 v5, v60 offset:36876
	s_waitcnt lgkmcnt(0)
	v_add_f32_e32 v4, v4, v5
	ds_read_b32 v5, v61 offset:36876
	s_waitcnt lgkmcnt(0)
	v_add_f32_e32 v4, v4, v5
	ds_read_b32 v5, v62 offset:36876
	s_waitcnt lgkmcnt(0)
	v_add_f32_e32 v4, v4, v5
	ds_read_b32 v5, v63 offset:36876
	s_waitcnt lgkmcnt(0)
	v_add_f32_e32 v4, v4, v5
	ds_read_b32 v5, v64 offset:36876
	s_waitcnt lgkmcnt(0)
	v_add_f32_e32 v4, v4, v5
	ds_read_b32 v5, v65 offset:36876
	s_waitcnt lgkmcnt(0)
; DI void phase_ada(const float* c_in, const float* cctx_in, const float* w_ada, const float* b_ada, unsigned char* ws, unsigned char* lds) {
;     ...
; #pragma unroll
;             for (int r = 0; r < 9; ++r) {
;                 float s = 0.f;
; #pragma unroll
;                 for (int g = 0; g < 16; ++g) s += red[(g * 128 + tid) * 9 + r];
;                 modt[((size_t)l * 9 + r) * 6144 + col] = s + bb;
;             }
	v_add_f32_e32 v4, v4, v5
	ds_read_b32 v5, v66 offset:36876
	s_waitcnt lgkmcnt(0)
	v_add_f32_e32 v4, v4, v5
	ds_read_b32 v5, v67 offset:36876
	s_waitcnt lgkmcnt(0)
	v_add_f32_e32 v4, v4, v5
	v_add_f32_e32 v7, v6, v4
	v_add_co_u32_e32 v4, vcc, s38, v2
	s_nop 1
	v_addc_co_u32_e32 v5, vcc, 0, v3, vcc
	flat_store_dword v[4:5], v7
	ds_read_b32 v4, v0 offset:36880
	ds_read_b32 v5, v0 offset:41488
	s_waitcnt lgkmcnt(0)
	v_add_f32_e32 v4, 0, v4
	v_add_f32_e32 v4, v4, v5
	ds_read_b32 v5, v0 offset:46096
	s_waitcnt lgkmcnt(0)
	v_add_f32_e32 v4, v4, v5
	ds_read_b32 v5, v0 offset:50704
	s_waitcnt lgkmcnt(0)
	v_add_f32_e32 v4, v4, v5
	ds_read_b32 v5, v0 offset:55312
	s_waitcnt lgkmcnt(0)
	v_add_f32_e32 v4, v4, v5
	ds_read_b32 v5, v0 offset:59920
	s_waitcnt lgkmcnt(0)
	v_add_f32_e32 v4, v4, v5
	ds_read_b32 v5, v0 offset:64528
	s_waitcnt lgkmcnt(0)
	v_add_f32_e32 v4, v4, v5
	ds_read_b32 v5, v59 offset:36880
	s_waitcnt lgkmcnt(0)
	v_add_f32_e32 v4, v4, v5
	ds_read_b32 v5, v60 offset:36880
	s_waitcnt lgkmcnt(0)
	v_add_f32_e32 v4, v4, v5
	ds_read_b32 v5, v61 offset:36880
	s_waitcnt lgkmcnt(0)
	v_add_f32_e32 v4, v4, v5
	ds_read_b32 v5, v62 offset:36880
	s_waitcnt lgkmcnt(0)
	v_add_f32_e32 v4, v4, v5
	ds_read_b32 v5, v63 offset:36880
	s_waitcnt lgkmcnt(0)
	v_add_f32_e32 v4, v4, v5
	ds_read_b32 v5, v64 offset:36880
	s_waitcnt lgkmcnt(0)
	v_add_f32_e32 v4, v4, v5
	ds_read_b32 v5, v65 offset:36880
	s_waitcnt lgkmcnt(0)
	v_add_f32_e32 v4, v4, v5
	ds_read_b32 v5, v66 offset:36880
	s_waitcnt lgkmcnt(0)
	v_add_f32_e32 v4, v4, v5
	ds_read_b32 v5, v67 offset:36880
	s_waitcnt lgkmcnt(0)
	v_add_f32_e32 v4, v4, v5
	v_add_f32_e32 v7, v6, v4
	v_add_co_u32_e32 v4, vcc, s39, v2
	s_nop 1
	v_addc_co_u32_e32 v5, vcc, 0, v3, vcc
	flat_store_dword v[4:5], v7
	ds_read_b32 v4, v0 offset:36884
	ds_read_b32 v5, v0 offset:41492
	s_waitcnt lgkmcnt(0)
	v_add_f32_e32 v4, 0, v4
	v_add_f32_e32 v4, v4, v5
	ds_read_b32 v5, v0 offset:46100
	s_waitcnt lgkmcnt(0)
	v_add_f32_e32 v4, v4, v5
	ds_read_b32 v5, v0 offset:50708
	s_waitcnt lgkmcnt(0)
	v_add_f32_e32 v4, v4, v5
	ds_read_b32 v5, v0 offset:55316
	s_waitcnt lgkmcnt(0)
	v_add_f32_e32 v4, v4, v5
	ds_read_b32 v5, v0 offset:59924
	s_waitcnt lgkmcnt(0)
	v_add_f32_e32 v4, v4, v5
	ds_read_b32 v5, v0 offset:64532
	s_waitcnt lgkmcnt(0)
	v_add_f32_e32 v4, v4, v5
	ds_read_b32 v5, v59 offset:36884
	s_waitcnt lgkmcnt(0)
	v_add_f32_e32 v4, v4, v5
	ds_read_b32 v5, v60 offset:36884
	s_waitcnt lgkmcnt(0)
	v_add_f32_e32 v4, v4, v5
	ds_read_b32 v5, v61 offset:36884
	s_waitcnt lgkmcnt(0)
	v_add_f32_e32 v4, v4, v5
	ds_read_b32 v5, v62 offset:36884
	s_waitcnt lgkmcnt(0)
	v_add_f32_e32 v4, v4, v5
	ds_read_b32 v5, v63 offset:36884
	s_waitcnt lgkmcnt(0)
	v_add_f32_e32 v4, v4, v5
	ds_read_b32 v5, v64 offset:36884
	s_waitcnt lgkmcnt(0)
	v_add_f32_e32 v4, v4, v5
	ds_read_b32 v5, v65 offset:36884
	s_waitcnt lgkmcnt(0)
	v_add_f32_e32 v4, v4, v5
	ds_read_b32 v5, v66 offset:36884
	s_waitcnt lgkmcnt(0)
	v_add_f32_e32 v4, v4, v5
	ds_read_b32 v5, v67 offset:36884
	s_waitcnt lgkmcnt(0)
	v_add_f32_e32 v4, v4, v5
	v_add_f32_e32 v7, v6, v4
	v_add_co_u32_e32 v4, vcc, s78, v2
	s_nop 1
	v_addc_co_u32_e32 v5, vcc, 0, v3, vcc
	flat_store_dword v[4:5], v7
	ds_read_b32 v4, v0 offset:36888
	ds_read_b32 v5, v0 offset:41496
	s_waitcnt lgkmcnt(0)
	v_add_f32_e32 v4, 0, v4
	v_add_f32_e32 v4, v4, v5
	ds_read_b32 v5, v0 offset:46104
	s_waitcnt lgkmcnt(0)
	v_add_f32_e32 v4, v4, v5
	ds_read_b32 v5, v0 offset:50712
	s_waitcnt lgkmcnt(0)
	v_add_f32_e32 v4, v4, v5
	ds_read_b32 v5, v0 offset:55320
	s_waitcnt lgkmcnt(0)
	v_add_f32_e32 v4, v4, v5
	ds_read_b32 v5, v0 offset:59928
	s_waitcnt lgkmcnt(0)
	v_add_f32_e32 v4, v4, v5
	ds_read_b32 v5, v0 offset:64536
	s_waitcnt lgkmcnt(0)
; DI void phase_ada(const float* c_in, const float* cctx_in, const float* w_ada, const float* b_ada, unsigned char* ws, unsigned char* lds) {
;     ...
; #pragma unroll
;             for (int r = 0; r < 9; ++r) {
;                 float s = 0.f;
; #pragma unroll
;                 for (int g = 0; g < 16; ++g) s += red[(g * 128 + tid) * 9 + r];
;                 modt[((size_t)l * 9 + r) * 6144 + col] = s + bb;
;             }
	v_add_f32_e32 v4, v4, v5
	ds_read_b32 v5, v59 offset:36888
	s_waitcnt lgkmcnt(0)
	v_add_f32_e32 v4, v4, v5
	ds_read_b32 v5, v60 offset:36888
	s_waitcnt lgkmcnt(0)
	v_add_f32_e32 v4, v4, v5
	ds_read_b32 v5, v61 offset:36888
	s_waitcnt lgkmcnt(0)
	v_add_f32_e32 v4, v4, v5
	ds_read_b32 v5, v62 offset:36888
	s_waitcnt lgkmcnt(0)
	v_add_f32_e32 v4, v4, v5
	ds_read_b32 v5, v63 offset:36888
	s_waitcnt lgkmcnt(0)
	v_add_f32_e32 v4, v4, v5
	ds_read_b32 v5, v64 offset:36888
	s_waitcnt lgkmcnt(0)
	v_add_f32_e32 v4, v4, v5
	ds_read_b32 v5, v65 offset:36888
	s_waitcnt lgkmcnt(0)
	v_add_f32_e32 v4, v4, v5
	ds_read_b32 v5, v66 offset:36888
	s_waitcnt lgkmcnt(0)
	v_add_f32_e32 v4, v4, v5
	ds_read_b32 v5, v67 offset:36888
	s_waitcnt lgkmcnt(0)
	v_add_f32_e32 v4, v4, v5
	v_add_f32_e32 v7, v6, v4
	v_add_co_u32_e32 v4, vcc, s79, v2
	s_nop 1
	v_addc_co_u32_e32 v5, vcc, 0, v3, vcc
	flat_store_dword v[4:5], v7
	ds_read_b32 v4, v0 offset:36892
	ds_read_b32 v5, v0 offset:41500
	s_waitcnt lgkmcnt(0)
	v_add_f32_e32 v4, 0, v4
	v_add_f32_e32 v4, v4, v5
	ds_read_b32 v5, v0 offset:46108
	s_waitcnt lgkmcnt(0)
	v_add_f32_e32 v4, v4, v5
	ds_read_b32 v5, v0 offset:50716
	s_waitcnt lgkmcnt(0)
	v_add_f32_e32 v4, v4, v5
	ds_read_b32 v5, v0 offset:55324
	s_waitcnt lgkmcnt(0)
	v_add_f32_e32 v4, v4, v5
	ds_read_b32 v5, v0 offset:59932
	s_waitcnt lgkmcnt(0)
	v_add_f32_e32 v4, v4, v5
	ds_read_b32 v5, v0 offset:64540
	s_waitcnt lgkmcnt(0)
	v_add_f32_e32 v4, v4, v5
	ds_read_b32 v5, v59 offset:36892
	s_waitcnt lgkmcnt(0)
	v_add_f32_e32 v4, v4, v5
	ds_read_b32 v5, v60 offset:36892
	s_waitcnt lgkmcnt(0)
	v_add_f32_e32 v4, v4, v5
	ds_read_b32 v5, v61 offset:36892
	s_waitcnt lgkmcnt(0)
	v_add_f32_e32 v4, v4, v5
	ds_read_b32 v5, v62 offset:36892
	s_waitcnt lgkmcnt(0)
	v_add_f32_e32 v4, v4, v5
	ds_read_b32 v5, v63 offset:36892
	s_waitcnt lgkmcnt(0)
	v_add_f32_e32 v4, v4, v5
	ds_read_b32 v5, v64 offset:36892
	s_waitcnt lgkmcnt(0)
	v_add_f32_e32 v4, v4, v5
	ds_read_b32 v5, v65 offset:36892
	s_waitcnt lgkmcnt(0)
	v_add_f32_e32 v4, v4, v5
	ds_read_b32 v5, v66 offset:36892
	s_waitcnt lgkmcnt(0)
	v_add_f32_e32 v4, v4, v5
	ds_read_b32 v5, v67 offset:36892
	s_waitcnt lgkmcnt(0)
	v_add_f32_e32 v4, v4, v5
	v_add_f32_e32 v7, v6, v4
	v_add_co_u32_e32 v4, vcc, s68, v2
	s_nop 1
	v_addc_co_u32_e32 v5, vcc, 0, v3, vcc
	flat_store_dword v[4:5], v7
	ds_read_b32 v4, v0 offset:36896
	ds_read_b32 v5, v0 offset:41504
	v_add_co_u32_e32 v2, vcc, 0x30000, v2
	s_waitcnt lgkmcnt(0)
	v_add_f32_e32 v4, 0, v4
	v_add_f32_e32 v4, v4, v5
	ds_read_b32 v5, v0 offset:46112
	v_addc_co_u32_e32 v3, vcc, 0, v3, vcc
	s_waitcnt lgkmcnt(0)
	v_add_f32_e32 v4, v4, v5
	ds_read_b32 v5, v0 offset:50720
	s_waitcnt lgkmcnt(0)
	v_add_f32_e32 v4, v4, v5
	ds_read_b32 v5, v0 offset:55328
	s_waitcnt lgkmcnt(0)
	v_add_f32_e32 v4, v4, v5
	ds_read_b32 v5, v0 offset:59936
	s_waitcnt lgkmcnt(0)
	v_add_f32_e32 v4, v4, v5
	ds_read_b32 v5, v0 offset:64544
	s_waitcnt lgkmcnt(0)
	v_add_f32_e32 v4, v4, v5
	ds_read_b32 v5, v59 offset:36896
	s_waitcnt lgkmcnt(0)
	v_add_f32_e32 v4, v4, v5
	ds_read_b32 v5, v60 offset:36896
	s_waitcnt lgkmcnt(0)
	v_add_f32_e32 v4, v4, v5
	ds_read_b32 v5, v61 offset:36896
	s_waitcnt lgkmcnt(0)
	v_add_f32_e32 v4, v4, v5
	ds_read_b32 v5, v62 offset:36896
	s_waitcnt lgkmcnt(0)
	v_add_f32_e32 v4, v4, v5
	ds_read_b32 v5, v63 offset:36896
	s_waitcnt lgkmcnt(0)
	v_add_f32_e32 v4, v4, v5
	ds_read_b32 v5, v64 offset:36896
	s_waitcnt lgkmcnt(0)
	v_add_f32_e32 v4, v4, v5
	ds_read_b32 v5, v65 offset:36896
	s_waitcnt lgkmcnt(0)
	v_add_f32_e32 v4, v4, v5
	ds_read_b32 v5, v66 offset:36896
	s_waitcnt lgkmcnt(0)
	v_add_f32_e32 v4, v4, v5
	ds_read_b32 v5, v67 offset:36896
	s_waitcnt lgkmcnt(0)
	v_add_f32_e32 v4, v4, v5
	v_add_f32_e32 v4, v6, v4
	flat_store_dword v[2:3], v4
	s_branch .LBB0_180
